# dilated attention: K and V tile loads prefetched with counted vmcnt, V pointers collapsed to two bases, spare registers via LDS spill
# baseline (speedup 1.0000x reference)
.Ldil_pro:
	v_lshlrev_b32_e32 v199, 7, v243
	ds_write_b128 v199, v[148:151]
	ds_write_b128 v199, v[152:155] offset:16
	ds_write_b128 v199, v[156:159] offset:32
	ds_write_b128 v199, v[160:163] offset:48
	ds_write_b128 v199, v[164:167] offset:64
	v_lshlrev_b32_e32 v132, s42, v197
	v_ashrrev_i32_e32 v133, 31, v132
	v_lshlrev_b64 v[132:133], 7, v[132:133]
	v_lshl_add_u64 v[132:133], v[14:15], 0, v[132:133]
	global_load_dwordx4 v[144:147], v[132:133], off offset:96
	global_load_dwordx4 v[140:143], v[132:133], off offset:64
	global_load_dwordx4 v[136:139], v[132:133], off offset:32
	s_nop 0
	global_load_dwordx4 v[132:135], v[132:133], off
	v_lshl_add_u64 v[236:237], v[236:237], 0, s[8:9]
	s_mov_b64 s[46:47], 0x2000
	v_lshl_add_u64 v[234:235], v[236:237], 0, s[46:47]
	global_load_dwordx4 v[214:217], v[236:237], off
	global_load_dwordx4 v[218:221], v[236:237], off offset:32
	global_load_dwordx4 v[222:225], v[236:237], off offset:2048
	global_load_dwordx4 v[226:229], v[236:237], off offset:2080
	global_load_dwordx4 v[230:233], v[234:235], off offset:-4096
	global_load_dwordx4 v[244:247], v[234:235], off offset:-4064
	global_load_dwordx4 v[248:251], v[234:235], off offset:-2048
	global_load_dwordx4 v[164:167], v[234:235], off offset:-2016
	global_load_dwordx4 v[148:151], v[234:235], off
	global_load_dwordx4 v[152:155], v[234:235], off offset:32
	global_load_dwordx4 v[156:159], v[234:235], off offset:2048
	global_load_dwordx4 v[200:203], v[234:235], off offset:2080
	s_waitcnt lgkmcnt(0)
.Ldil_top:
	s_waitcnt vmcnt(12)
	s_nop 0
	v_mfma_f32_32x32x16_bf16 v[112:127], v[132:135], v[2:5], 0
	v_mfma_f32_32x32x16_bf16 v[112:127], v[136:139], v[6:9], v[112:127]
	v_mfma_f32_32x32x16_bf16 v[112:127], v[140:143], v[10:13], v[112:127]
	v_mfma_f32_32x32x16_bf16 v[112:127], v[144:147], v[128:131], v[112:127]
	s_add_i32 s44, s44, 1
	v_add_u32_e32 v197, 32, v197
	s_cmp_lt_i32 s44, s43
	s_cbranch_scc0 .Ldil_nok
	v_lshlrev_b32_e32 v132, s42, v197
	v_ashrrev_i32_e32 v133, 31, v132
	v_lshlrev_b64 v[132:133], 7, v[132:133]
	v_lshl_add_u64 v[132:133], v[14:15], 0, v[132:133]
	global_load_dwordx4 v[144:147], v[132:133], off offset:96
	global_load_dwordx4 v[140:143], v[132:133], off offset:64
	global_load_dwordx4 v[136:139], v[132:133], off offset:32
	s_nop 0
	global_load_dwordx4 v[132:135], v[132:133], off
.Ldil_nok:
	s_nop 11
	v_max_f32_e32 v160, v113, v113
	v_max_f32_e32 v162, v112, v112
	v_max_f32_e32 v160, v162, v160
	v_max3_f32 v160, v160, v114, v115
	v_max3_f32 v160, v160, v116, v117
	v_max3_f32 v160, v160, v118, v119
	v_max3_f32 v160, v160, v120, v121
	v_max3_f32 v160, v160, v122, v123
	v_max3_f32 v160, v160, v124, v125
	v_max3_f32 v160, v160, v126, v127
	v_mov_b32_e32 v162, v160
	s_nop 1
	v_permlane32_swap_b32_e32 v160, v162
	v_max_f32_e32 v162, v162, v162
	v_max_f32_e32 v160, v160, v160
	v_max_f32_e32 v160, v160, v162
	v_add_f32_e32 v162, 0x42317218, v198
	v_cmp_gt_f32_e32 vcc, v160, v162
	s_cbranch_vccz .Ldil_soft
	s_nop 0
	v_cndmask_b32_e32 v162, v198, v160, vcc
	v_sub_f32_e32 v160, v198, v162
	v_mul_f32_e32 v160, 0x3e38aa3b, v160
	v_exp_f32_e32 v160, v160
	v_mov_b32_e32 v198, v162
	v_mul_f32_e32 v177, v177, v160
	v_pk_mul_f32 v[110:111], v[110:111], v[160:161] op_sel_hi:[1,0]
	v_pk_mul_f32 v[108:109], v[108:109], v[160:161] op_sel_hi:[1,0]
	v_pk_mul_f32 v[106:107], v[106:107], v[160:161] op_sel_hi:[1,0]
	v_pk_mul_f32 v[104:105], v[104:105], v[160:161] op_sel_hi:[1,0]
	v_pk_mul_f32 v[102:103], v[102:103], v[160:161] op_sel_hi:[1,0]
	v_pk_mul_f32 v[100:101], v[100:101], v[160:161] op_sel_hi:[1,0]
	v_pk_mul_f32 v[98:99], v[98:99], v[160:161] op_sel_hi:[1,0]
	v_pk_mul_f32 v[96:97], v[96:97], v[160:161] op_sel_hi:[1,0]
	v_pk_mul_f32 v[94:95], v[94:95], v[160:161] op_sel_hi:[1,0]
	v_pk_mul_f32 v[92:93], v[92:93], v[160:161] op_sel_hi:[1,0]
	v_pk_mul_f32 v[90:91], v[90:91], v[160:161] op_sel_hi:[1,0]
	v_pk_mul_f32 v[88:89], v[88:89], v[160:161] op_sel_hi:[1,0]
	v_pk_mul_f32 v[86:87], v[86:87], v[160:161] op_sel_hi:[1,0]
	v_pk_mul_f32 v[84:85], v[84:85], v[160:161] op_sel_hi:[1,0]
	v_pk_mul_f32 v[82:83], v[82:83], v[160:161] op_sel_hi:[1,0]
	v_pk_mul_f32 v[80:81], v[80:81], v[160:161] op_sel_hi:[1,0]
	v_pk_mul_f32 v[78:79], v[78:79], v[160:161] op_sel_hi:[1,0]
	v_pk_mul_f32 v[76:77], v[76:77], v[160:161] op_sel_hi:[1,0]
	v_pk_mul_f32 v[74:75], v[74:75], v[160:161] op_sel_hi:[1,0]
	v_pk_mul_f32 v[72:73], v[72:73], v[160:161] op_sel_hi:[1,0]
	v_pk_mul_f32 v[70:71], v[70:71], v[160:161] op_sel_hi:[1,0]
	v_pk_mul_f32 v[68:69], v[68:69], v[160:161] op_sel_hi:[1,0]
	v_pk_mul_f32 v[66:67], v[66:67], v[160:161] op_sel_hi:[1,0]
	v_pk_mul_f32 v[64:65], v[64:65], v[160:161] op_sel_hi:[1,0]
	v_pk_mul_f32 v[62:63], v[62:63], v[160:161] op_sel_hi:[1,0]
	v_pk_mul_f32 v[60:61], v[60:61], v[160:161] op_sel_hi:[1,0]
	v_pk_mul_f32 v[58:59], v[58:59], v[160:161] op_sel_hi:[1,0]
	v_pk_mul_f32 v[56:57], v[56:57], v[160:161] op_sel_hi:[1,0]
	v_pk_mul_f32 v[54:55], v[54:55], v[160:161] op_sel_hi:[1,0]
	v_pk_mul_f32 v[52:53], v[52:53], v[160:161] op_sel_hi:[1,0]
	v_pk_mul_f32 v[50:51], v[50:51], v[160:161] op_sel_hi:[1,0]
	v_pk_mul_f32 v[48:49], v[48:49], v[160:161] op_sel_hi:[1,0]
	v_pk_mul_f32 v[46:47], v[46:47], v[160:161] op_sel_hi:[1,0]
	v_pk_mul_f32 v[44:45], v[44:45], v[160:161] op_sel_hi:[1,0]
	v_pk_mul_f32 v[42:43], v[42:43], v[160:161] op_sel_hi:[1,0]
	v_pk_mul_f32 v[40:41], v[40:41], v[160:161] op_sel_hi:[1,0]
	v_pk_mul_f32 v[38:39], v[38:39], v[160:161] op_sel_hi:[1,0]
	v_pk_mul_f32 v[36:37], v[36:37], v[160:161] op_sel_hi:[1,0]
	v_pk_mul_f32 v[34:35], v[34:35], v[160:161] op_sel_hi:[1,0]
	v_pk_mul_f32 v[32:33], v[32:33], v[160:161] op_sel_hi:[1,0]
	v_pk_mul_f32 v[30:31], v[30:31], v[160:161] op_sel_hi:[1,0]
	v_pk_mul_f32 v[28:29], v[28:29], v[160:161] op_sel_hi:[1,0]
	v_pk_mul_f32 v[26:27], v[26:27], v[160:161] op_sel_hi:[1,0]
	v_pk_mul_f32 v[24:25], v[24:25], v[160:161] op_sel_hi:[1,0]
	v_pk_mul_f32 v[22:23], v[22:23], v[160:161] op_sel_hi:[1,0]
	v_pk_mul_f32 v[20:21], v[20:21], v[160:161] op_sel_hi:[1,0]
	v_pk_mul_f32 v[18:19], v[18:19], v[160:161] op_sel_hi:[1,0]
	v_pk_mul_f32 v[16:17], v[16:17], v[160:161] op_sel_hi:[1,0]
.Ldil_soft:
	v_mul_f32_e32 v160, 0xbe38aa3b, v198
	v_fmamk_f32 v112, v112, 0x3e38aa3b, v160
	v_exp_f32_e32 v112, v112
	v_fmamk_f32 v113, v113, 0x3e38aa3b, v160
	v_exp_f32_e32 v113, v113
	v_fmamk_f32 v114, v114, 0x3e38aa3b, v160
	v_exp_f32_e32 v114, v114
	v_fmamk_f32 v115, v115, 0x3e38aa3b, v160
	v_cmp_gt_u32_e32 vcc, s75, v0
	v_add_u32_e32 v163, -1, v0
	v_exp_f32_e32 v115, v115
	v_fmamk_f32 v116, v116, 0x3e38aa3b, v160
	v_cndmask_b32_e32 v112, 0, v112, vcc
	v_cmp_gt_u32_e32 vcc, s75, v163
	v_add_u32_e32 v163, -2, v0
	v_exp_f32_e32 v116, v116
	v_fmamk_f32 v117, v117, 0x3e38aa3b, v160
	v_add_f32_e32 v162, 0, v112
	v_cndmask_b32_e32 v113, 0, v113, vcc
	v_cmp_gt_u32_e32 vcc, s75, v163
	v_add_u32_e32 v163, -3, v0
	v_exp_f32_e32 v117, v117
	v_fmamk_f32 v118, v118, 0x3e38aa3b, v160
	v_add_f32_e32 v162, v113, v162
	v_cndmask_b32_e32 v114, 0, v114, vcc
	v_cmp_gt_u32_e32 vcc, s75, v163
	v_add_u32_e32 v163, -4, v0
	v_exp_f32_e32 v118, v118
	v_fmamk_f32 v119, v119, 0x3e38aa3b, v160
	v_add_f32_e32 v162, v114, v162
	v_cndmask_b32_e32 v115, 0, v115, vcc
	v_cmp_gt_u32_e32 vcc, s75, v163
	v_add_u32_e32 v163, -5, v0
	v_exp_f32_e32 v119, v119
	v_fmamk_f32 v120, v120, 0x3e38aa3b, v160
	v_add_f32_e32 v162, v115, v162
	v_cndmask_b32_e32 v116, 0, v116, vcc
	v_cmp_gt_u32_e32 vcc, s75, v163
	v_add_u32_e32 v163, -6, v0
	v_exp_f32_e32 v120, v120
	v_fmamk_f32 v121, v121, 0x3e38aa3b, v160
	v_add_f32_e32 v162, v116, v162
	v_cndmask_b32_e32 v117, 0, v117, vcc
	v_cmp_gt_u32_e32 vcc, s75, v163
	v_add_u32_e32 v163, -7, v0
	v_exp_f32_e32 v121, v121
	v_fmamk_f32 v122, v122, 0x3e38aa3b, v160
	v_add_f32_e32 v162, v117, v162
	v_cndmask_b32_e32 v118, 0, v118, vcc
	v_cmp_gt_u32_e32 vcc, s75, v163
	v_add_u32_e32 v163, -16, v0
	v_exp_f32_e32 v122, v122
	v_fmamk_f32 v123, v123, 0x3e38aa3b, v160
	v_add_f32_e32 v162, v118, v162
	v_cndmask_b32_e32 v119, 0, v119, vcc
	v_cmp_gt_u32_e32 vcc, s75, v163
	v_subrev_u32_e32 v163, 17, v0
	v_exp_f32_e32 v123, v123
	v_fmamk_f32 v124, v124, 0x3e38aa3b, v160
	v_add_f32_e32 v162, v119, v162
	v_cndmask_b32_e32 v120, 0, v120, vcc
	v_cmp_gt_u32_e32 vcc, s75, v163
	v_subrev_u32_e32 v163, 18, v0
	v_exp_f32_e32 v124, v124
	v_fmamk_f32 v125, v125, 0x3e38aa3b, v160
	v_add_f32_e32 v162, v120, v162
	v_cndmask_b32_e32 v121, 0, v121, vcc
	v_cmp_gt_u32_e32 vcc, s75, v163
	v_subrev_u32_e32 v163, 19, v0
	v_exp_f32_e32 v125, v125
	v_fmamk_f32 v126, v126, 0x3e38aa3b, v160
	v_add_f32_e32 v162, v121, v162
	v_cndmask_b32_e32 v122, 0, v122, vcc
	v_cmp_gt_u32_e32 vcc, s75, v163
	v_subrev_u32_e32 v163, 20, v0
	v_exp_f32_e32 v126, v126
	v_fmac_f32_e32 v160, 0x3e38aa3b, v127
	v_add_f32_e32 v162, v122, v162
	v_cndmask_b32_e32 v123, 0, v123, vcc
	v_cmp_gt_u32_e32 vcc, s75, v163
	v_subrev_u32_e32 v163, 21, v0
	v_exp_f32_e32 v127, v160
	v_add_f32_e32 v162, v123, v162
	v_cndmask_b32_e32 v124, 0, v124, vcc
	v_cmp_gt_u32_e32 vcc, s75, v163
	v_subrev_u32_e32 v163, 22, v0
	v_add_f32_e32 v162, v124, v162
	v_cndmask_b32_e32 v125, 0, v125, vcc
	v_cmp_gt_u32_e32 vcc, s75, v163
	v_subrev_u32_e32 v160, 23, v0
	v_add_f32_e32 v162, v125, v162
	v_cndmask_b32_e32 v126, 0, v126, vcc
	v_cmp_gt_u32_e32 vcc, s75, v160
	v_add_f32_e32 v162, v126, v162
	v_cndmask_b32_e32 v127, 0, v127, vcc
	v_add_f32_e32 v160, v127, v162
	v_add_f32_e32 v177, v177, v160
	v_cvt_pk_bf16_f32 v112, v112, v113
	v_cvt_pk_bf16_f32 v113, v114, v115
	v_cvt_pk_bf16_f32 v114, v116, v117
	v_cvt_pk_bf16_f32 v115, v118, v119
	v_cvt_pk_bf16_f32 v116, v120, v121
	v_cvt_pk_bf16_f32 v118, v124, v125
	v_cvt_pk_bf16_f32 v117, v122, v123
	v_cvt_pk_bf16_f32 v119, v126, v127
	s_cmp_lt_i32 s44, s43
	s_cbranch_scc0 .Ldil_w0
	s_waitcnt vmcnt(4)
	s_branch .Ldil_pv

.Ldil_pv:
	s_nop 0
	v_mfma_f32_32x32x16_bf16 v[96:111], v[214:217], v[112:115], v[96:111]
	v_mfma_f32_32x32x16_bf16 v[80:95], v[222:225], v[112:115], v[80:95]
	v_mfma_f32_32x32x16_bf16 v[64:79], v[230:233], v[112:115], v[64:79]
	v_mfma_f32_32x32x16_bf16 v[48:63], v[248:251], v[112:115], v[48:63]
	v_mfma_f32_32x32x16_bf16 v[32:47], v[148:151], v[112:115], v[32:47]
	v_mfma_f32_32x32x16_bf16 v[16:31], v[156:159], v[112:115], v[16:31]
	v_mfma_f32_32x32x16_bf16 v[96:111], v[218:221], v[116:119], v[96:111]
	v_mfma_f32_32x32x16_bf16 v[80:95], v[226:229], v[116:119], v[80:95]
	v_mfma_f32_32x32x16_bf16 v[64:79], v[244:247], v[116:119], v[64:79]
	v_mfma_f32_32x32x16_bf16 v[48:63], v[164:167], v[116:119], v[48:63]
	v_mfma_f32_32x32x16_bf16 v[32:47], v[152:155], v[116:119], v[32:47]
	v_mfma_f32_32x32x16_bf16 v[16:31], v[200:203], v[116:119], v[16:31]
	v_subrev_u32_e32 v0, 32, v0
	s_mov_b64 s[46:47], 0x3000
	v_lshl_add_u64 v[236:237], v[236:237], 0, s[46:47]
	v_lshl_add_u64 v[234:235], v[234:235], 0, s[46:47]
	s_cmp_lt_i32 s44, s43
	s_cbranch_scc0 .Ldil_exit
	global_load_dwordx4 v[214:217], v[236:237], off
	global_load_dwordx4 v[218:221], v[236:237], off offset:32
	global_load_dwordx4 v[222:225], v[236:237], off offset:2048
	global_load_dwordx4 v[226:229], v[236:237], off offset:2080
	global_load_dwordx4 v[230:233], v[234:235], off offset:-4096
	global_load_dwordx4 v[244:247], v[234:235], off offset:-4064
	global_load_dwordx4 v[248:251], v[234:235], off offset:-2048
	global_load_dwordx4 v[164:167], v[234:235], off offset:-2016
	global_load_dwordx4 v[148:151], v[234:235], off
	global_load_dwordx4 v[152:155], v[234:235], off offset:32
	global_load_dwordx4 v[156:159], v[234:235], off offset:2048
	global_load_dwordx4 v[200:203], v[234:235], off offset:2080
	s_branch .Ldil_top
.Ldil_exit:
	v_lshlrev_b32_e32 v199, 7, v243
	ds_read_b128 v[148:151], v199
	ds_read_b128 v[152:155], v199 offset:16
	ds_read_b128 v[156:159], v199 offset:32
	ds_read_b128 v[160:163], v199 offset:48
	ds_read_b128 v[164:167], v199 offset:64
	s_waitcnt lgkmcnt(0)
	s_branch .LBB0_878
